# P2 E7: transposed bf16 copies written as 16 dword stores per thread (token pairs packed via DPP row shifts + v_perm_b32) instead of 32 two-byte stores
# baseline (speedup 1.0000x reference)
; __device__ __forceinline__ float fexp(float x) { return __builtin_amdgcn_exp2f(x * 1.44269504088896f); }
; __device__ void rwkv_prep_item(const Params& p, char* lds_, int item, PrepRaw& raw, int next_item) {
;     ...
;   {
;     const int d = tid & 63, seg = tid >> 6;
;     float pre = 0.f;
;     for (int q = 0; q < seg; ++q) pre += Za[q * 64 + d];
; #pragma unroll
;     for (int q = 0; q < 8; ++q) { pre += G[(seg * 8 + q) * 68 + d]; G[(seg * 8 + q) * 68 + d] = pre; }
;   }
;   __syncthreads();
;   {
;     float a_[8], b_[8], k_[8], r_[8];
; #pragma unroll
;     for (int e = 0; e < 8; ++e) {
;       const float g = G[t * 68 + cg8 + e];
;       const float eg = fexp(g), egm = fexp(g - lw[e]), ei = fexp(-g);
;       a_[e] = av[e] * egm; b_[e] = bv[e] * ei; k_[e] = k2[e] * ei; r_[e] = rr[e] * eg;
;       if (t == 63) gC[cg8 + e] = eg;
;     }
.LBB0_303:
	s_or_b64 exec, exec, s[58:59]
	ds_read2_b32 v[60:61], v252 offset1:68
	ds_read2_b32 v[74:75], v252 offset0:136 offset1:204
	ds_read2_b32 v[76:77], v58 offset0:16 offset1:84
	ds_read2_b32 v[84:85], v58 offset0:152 offset1:220
	s_waitcnt lgkmcnt(3)
	v_add_f32_e32 v59, v59, v60
	v_add_f32_e32 v60, v59, v61
	ds_write2_b32 v252, v59, v60 offset1:68
	s_waitcnt lgkmcnt(3)
	v_add_f32_e32 v59, v60, v74
	v_add_f32_e32 v60, v59, v75
	ds_write2_b32 v252, v59, v60 offset0:136 offset1:204
	s_waitcnt lgkmcnt(3)
	v_add_f32_e32 v59, v60, v76
	v_add_f32_e32 v60, v59, v77
	ds_write2_b32 v58, v59, v60 offset0:16 offset1:84
	s_waitcnt lgkmcnt(3)
	v_add_f32_e32 v59, v60, v84
	v_add_f32_e32 v60, v59, v85
	ds_write2_b32 v58, v59, v60 offset0:152 offset1:220
	s_waitcnt lgkmcnt(0)
	s_barrier
	ds_read_b32 v61, v181
	ds_read_b32 v60, v181 offset:4
	ds_read_b32 v77, v181 offset:8
	ds_read_b32 v76, v181 offset:12
	ds_read_b32 v93, v181 offset:16
	ds_read_b32 v92, v181 offset:20
	ds_read_b32 v97, v181 offset:24
	ds_read_b32 v96, v181 offset:28
	s_waitcnt lgkmcnt(7)
	v_mul_f32_e32 v58, 0x3fb8aa3b, v61
	v_exp_f32_e32 v59, v58
	s_waitcnt lgkmcnt(6)
	v_mul_f32_e32 v58, 0x3fb8aa3b, v60
	v_exp_f32_e32 v58, v58
	s_waitcnt lgkmcnt(5)
	v_mul_f32_e32 v74, 0x3fb8aa3b, v77
	v_exp_f32_e32 v75, v74
	s_waitcnt lgkmcnt(4)
	v_mul_f32_e32 v74, 0x3fb8aa3b, v76
	v_exp_f32_e32 v74, v74
	s_waitcnt lgkmcnt(3)
	v_mul_f32_e32 v84, 0x3fb8aa3b, v93
	v_exp_f32_e32 v85, v84
	s_waitcnt lgkmcnt(2)
	v_mul_f32_e32 v84, 0x3fb8aa3b, v92
	v_exp_f32_e32 v84, v84
	s_waitcnt lgkmcnt(1)
	v_mul_f32_e32 v94, 0x3fb8aa3b, v97
	v_exp_f32_e32 v95, v94
	s_waitcnt lgkmcnt(0)
	v_mul_f32_e32 v94, 0x3fb8aa3b, v96
	v_exp_f32_e32 v94, v94
	s_and_saveexec_b64 s[58:59], s[8:9]
	ds_write_b32 v183, v59
	ds_write_b32 v183, v58 offset:4
	ds_write_b32 v183, v75 offset:8
	ds_write_b32 v183, v74 offset:12
	ds_write_b32 v183, v85 offset:16
	ds_write_b32 v183, v84 offset:20
	ds_write_b32 v183, v95 offset:24
	ds_write_b32 v183, v94 offset:28
	s_or_b64 exec, exec, s[58:59]
	v_lshlrev_b32_e32 v98, 16, v18
	v_and_b32_e32 v99, 0xffff0000, v18
	v_lshlrev_b32_e32 v100, 16, v22
	v_and_b32_e32 v101, 0xffff0000, v22
	v_lshlrev_b32_e32 v18, 16, v19
	v_and_b32_e32 v19, 0xffff0000, v19
	v_lshlrev_b32_e32 v22, 16, v23
	v_and_b32_e32 v23, 0xffff0000, v23
	v_pk_add_f32 v[22:23], v[22:23], v[18:19] neg_lo:[0,1] neg_hi:[0,1]
	v_pk_add_f32 v[100:101], v[100:101], v[98:99] neg_lo:[0,1] neg_hi:[0,1]
	v_pk_fma_f32 v[18:19], v[32:33], v[22:23], v[18:19]
	v_lshlrev_b32_e32 v22, 16, v20
	v_and_b32_e32 v23, 0xffff0000, v20
	v_lshlrev_b32_e32 v32, 16, v24
	v_and_b32_e32 v33, 0xffff0000, v24
	v_lshlrev_b32_e32 v24, 16, v25
	v_and_b32_e32 v25, 0xffff0000, v25
	v_lshlrev_b32_e32 v20, 16, v21
	v_and_b32_e32 v21, 0xffff0000, v21
	v_pk_add_f32 v[32:33], v[32:33], v[22:23] neg_lo:[0,1] neg_hi:[0,1]
	v_pk_add_f32 v[24:25], v[24:25], v[20:21] neg_lo:[0,1] neg_hi:[0,1]
	v_pk_fma_f32 v[30:31], v[30:31], v[100:101], v[98:99]
	v_pk_fma_f32 v[22:23], v[26:27], v[32:33], v[22:23]
	v_pk_fma_f32 v[20:21], v[28:29], v[24:25], v[20:21]
	s_and_b64 vcc, exec, s[76:77]
	s_cbranch_vccz .LBB0_321
; __device__ __forceinline__ unsigned pk2(float lo, float hi) { f32x2_t v = {lo, hi}; bf16x2_t b = __builtin_convertvector(v, bf16x2_t); return __builtin_bit_cast(unsigned, b); }
; __device__ __forceinline__ float fexp(float x) { return __builtin_amdgcn_exp2f(x * 1.44269504088896f); }
; __device__ void rwkv_prep_item(const Params& p, char* lds_, int item, PrepRaw& raw, int next_item) {
;     ...
;     const float inv = __builtin_amdgcn_rsqf(fmaxf(ss, 1e-24f));
; #pragma unroll
;     for (int e = 0; e < 8; ++e) { const float kn = kk[e] * inv; av[e] = -kn; bv[e] = kn * ai[e]; }
;   }
;   __builtin_amdgcn_sched_barrier(0);
;   if (next_item < 4096) prep_load(p, next_item, raw);
;   __builtin_amdgcn_sched_barrier(0);
;   __syncthreads();
; #pragma unroll
;   for (int e = 0; e < 8; ++e) G[t * 68 + cg8 + e] = lw[e];
;   __syncthreads();
;   {
;     const int d = tid & 63, seg = tid >> 6;
;     float s = 0.f;
; #pragma unroll
;     for (int q = 0; q < 8; ++q) s += G[(seg * 8 + q) * 68 + d];
;     Za[seg * 64 + d] = s;
;   }
;   __syncthreads();
;   {
;     const int d = tid & 63, seg = tid >> 6;
;     float pre = 0.f;
;     for (int q = 0; q < seg; ++q) pre += Za[q * 64 + d];
; #pragma unroll
;     for (int q = 0; q < 8; ++q) { pre += G[(seg * 8 + q) * 68 + d]; G[(seg * 8 + q) * 68 + d] = pre; }
;   }
;   __syncthreads();
;   {
;     float a_[8], b_[8], k_[8], r_[8];
; #pragma unroll
;     for (int e = 0; e < 8; ++e) {
;       const float g = G[t * 68 + cg8 + e];
;       const float eg = fexp(g), egm = fexp(g - lw[e]), ei = fexp(-g);
;       a_[e] = av[e] * egm; b_[e] = bv[e] * ei; k_[e] = k2[e] * ei; r_[e] = rr[e] * eg;
;       if (t == 63) gC[cg8 + e] = eg;
;     }
;     auto put = [&](u16* rowm, u16* trans, const float (&f)[8]) {
;       const unsigned wv[4] = {pk2(f[0], f[1]), pk2(f[2], f[3]), pk2(f[4], f[5]), pk2(f[6], f[7])};
;       if (rowm) { u32x4 w4; w4.x = wv[0]; w4.y = wv[1]; w4.z = wv[2]; w4.w = wv[3]; *(u32x4*)(rowm + t * LD + cg8) = w4; }
;       if (trans) {
; #pragma unroll
;         for (int e = 0; e < 8; ++e) trans[(cg8 + e) * LD + (((t >> 3) ^ (cg8 >> 3)) << 3) + (t & 7)] = (u16)((e & 1) ? (wv[e >> 1] >> 16) : (wv[e >> 1] & 0xffffu));
;       }
;     };
;     put(At, AT, a_); put(Bt, BT, b_); put(Kt, KT, k_); put(Rt, nullptr, r_); put(nullptr, VT, vv);
	v_add_f32_e32 v24, v80, v81
	v_max_f32_e32 v24, 0x179abe15, v24
	v_rsq_f32_e32 v24, v24
	v_sub_f32_e32 v25, v97, v40
	v_mul_f32_e32 v26, 0xbfb8aa3b, v97
	v_mul_f32_e32 v25, 0x3fb8aa3b, v25
	v_exp_f32_e32 v26, v26
	v_exp_f32_e32 v25, v25
	v_mul_f32_e32 v27, v56, v24
	v_mul_f32_e32 v28, v51, v27
	v_mul_f32_e32 v28, v28, v26
	v_mul_f32_e32 v29, v52, v26
	v_sub_f32_e32 v26, v96, v41
	v_mul_f32_e64 v25, v25, -v27
	v_mul_f32_e32 v26, 0x3fb8aa3b, v26
	v_mul_f32_e32 v27, 0xbfb8aa3b, v96
	v_exp_f32_e32 v26, v26
	v_exp_f32_e32 v27, v27
	v_mul_f32_e32 v33, v79, v24
	v_mul_f32_e32 v40, v57, v33
	v_mul_f32_e64 v26, v26, -v33
	v_mul_f32_e32 v33, v40, v27
	v_mul_f32_e32 v40, v53, v27
	v_sub_f32_e32 v27, v93, v38
	v_mul_f32_e32 v27, 0x3fb8aa3b, v27
	v_exp_f32_e32 v27, v27
	v_mul_f32_e32 v51, v78, v24
	v_mul_f32_e32 v52, v54, v51
	v_mul_f32_e32 v53, v55, v24
	v_mul_f32_e64 v51, v27, -v51
	v_sub_f32_e32 v27, v92, v39
	v_mul_f32_e32 v27, 0x3fb8aa3b, v27
	v_exp_f32_e32 v27, v27
	v_mul_f32_e32 v50, v50, v53
	v_mul_f32_e32 v54, v68, v24
	v_mul_f32_e32 v55, v72, v54
	v_mul_f32_e64 v53, v27, -v53
	v_sub_f32_e32 v27, v77, v36
	v_mul_f32_e32 v27, 0x3fb8aa3b, v27
	v_exp_f32_e32 v27, v27
	v_mul_f32_e32 v36, 0xbfb8aa3b, v77
	v_exp_f32_e32 v36, v36
	v_mul_f32_e32 v57, v69, v24
	v_mul_f32_e64 v54, v27, -v54
	v_sub_f32_e32 v27, v76, v37
	v_mul_f32_e32 v27, 0x3fb8aa3b, v27
	v_exp_f32_e32 v27, v27
	v_mul_f32_e32 v55, v55, v36
	v_mul_f32_e32 v36, v64, v36
	v_mul_f32_e32 v64, v73, v57
	v_mul_f32_e64 v57, v27, -v57
	v_sub_f32_e32 v27, v61, v34
	v_mul_f32_e32 v27, 0x3fb8aa3b, v27
	v_exp_f32_e32 v27, v27
	v_mul_f32_e32 v34, 0xbfb8aa3b, v61
	v_mul_f32_e32 v61, v66, v24
	v_mul_f32_e32 v66, v70, v61
	v_mul_f32_e64 v61, v27, -v61
	v_sub_f32_e32 v27, v60, v35
	v_mul_f32_e32 v27, 0x3fb8aa3b, v27
	v_mul_f32_e32 v38, 0xbfb8aa3b, v93
	v_mul_f32_e32 v39, 0xbfb8aa3b, v92
	v_mul_f32_e32 v37, 0xbfb8aa3b, v76
	v_exp_f32_e32 v27, v27
	v_mul_f32_e32 v35, 0xbfb8aa3b, v60
	v_exp_f32_e32 v38, v38
	v_exp_f32_e32 v39, v39
	v_exp_f32_e32 v37, v37
	v_exp_f32_e32 v34, v34
	v_exp_f32_e32 v35, v35
	v_mul_f32_e32 v24, v67, v24
	v_mul_f32_e32 v60, v71, v24
	v_mul_f32_e64 v24, v27, -v24
	v_mul_f32_e32 v52, v52, v38
	v_mul_f32_e32 v50, v50, v39
	v_mul_f32_e32 v64, v64, v37
	v_mul_f32_e32 v66, v66, v34
	v_mul_f32_e32 v60, v60, v35
	v_cvt_pk_bf16_f32 v27, v25, v26
	v_cvt_pk_bf16_f32 v26, v51, v53
	v_cvt_pk_bf16_f32 v25, v54, v57
	v_cvt_pk_bf16_f32 v24, v61, v24
	v_mul_f32_e32 v38, v46, v38
	v_mul_f32_e32 v39, v47, v39
	v_mul_f32_e32 v37, v65, v37
	v_mul_f32_e32 v34, v62, v34
	v_mul_f32_e32 v35, v63, v35
	ds_write_b128 v184, v[24:27] offset:256
	v_and_b32_e32 v99, 8, v223
	v_cmp_ne_u32_e64 s[94:95], 0, v99
	v_mov_b32_e32 v100, 0x05040100
	v_mov_b32_e32 v101, 0x01000504
	v_mov_b32_e32 v102, 0x07060302
	v_mov_b32_e32 v103, 0x03020706
	v_cndmask_b32_e64 v96, v100, v101, s[94:95]
	v_cndmask_b32_e64 v97, v102, v103, s[94:95]
	v_mov_b32_e32 v100, 0x23e
	v_cndmask_b32_e64 v100, 0, v100, s[94:95]
	v_add_u32_e32 v98, v185, v100
	v_cndmask_b32_e64 v104, v24, v26, s[94:95]
	v_cndmask_b32_e64 v105, v25, v27, s[94:95]
	v_mov_b32_dpp v106, v24 row_shl:8 row_mask:0xf bank_mask:0x3
	v_mov_b32_dpp v107, v25 row_shl:8 row_mask:0xf bank_mask:0x3
	v_mov_b32_dpp v106, v26 row_shr:8 row_mask:0xf bank_mask:0xc
	v_mov_b32_dpp v107, v27 row_shr:8 row_mask:0xf bank_mask:0xc
	s_nop 1
	v_perm_b32 v108, v106, v104, v96
	v_perm_b32 v109, v106, v104, v97
	v_perm_b32 v110, v107, v105, v96
	v_perm_b32 v111, v107, v105, v97
	ds_write_b32 v98, v108 offset:37120
	ds_write_b32 v98, v109 offset:37264
	ds_write_b32 v98, v110 offset:37408
	ds_write_b32 v98, v111 offset:37552
	v_cvt_pk_bf16_f32 v24, v66, v60
	v_cvt_pk_bf16_f32 v25, v55, v64
	v_cvt_pk_bf16_f32 v26, v52, v50
	v_cvt_pk_bf16_f32 v27, v28, v33
	v_mul_f32_e32 v32, v83, v95
	v_mul_f32_e32 v41, v82, v94
	v_mul_f32_e32 v46, v89, v85
	v_mul_f32_e32 v47, v88, v84
	v_mul_f32_e32 v56, v87, v75
	v_mul_f32_e32 v65, v86, v74
	v_mul_f32_e32 v59, v91, v59
	v_mul_f32_e32 v58, v90, v58
	ds_write_b128 v184, v[24:27] offset:9472
	v_cndmask_b32_e64 v104, v24, v26, s[94:95]
	v_cndmask_b32_e64 v105, v25, v27, s[94:95]
	v_mov_b32_dpp v106, v24 row_shl:8 row_mask:0xf bank_mask:0x3
	v_mov_b32_dpp v107, v25 row_shl:8 row_mask:0xf bank_mask:0x3
	v_mov_b32_dpp v106, v26 row_shr:8 row_mask:0xf bank_mask:0xc
	v_mov_b32_dpp v107, v27 row_shr:8 row_mask:0xf bank_mask:0xc
	s_nop 1
	v_perm_b32 v108, v106, v104, v96
	v_perm_b32 v109, v106, v104, v97
	v_perm_b32 v110, v107, v105, v96
	v_perm_b32 v111, v107, v105, v97
	ds_write_b32 v98, v108 offset:46336
	ds_write_b32 v98, v109 offset:46480
	ds_write_b32 v98, v110 offset:46624
	ds_write_b32 v98, v111 offset:46768
	v_cvt_pk_bf16_f32 v27, v29, v40
	v_cvt_pk_bf16_f32 v26, v38, v39
	v_cvt_pk_bf16_f32 v25, v36, v37
	v_cvt_pk_bf16_f32 v24, v34, v35
	ds_write_b128 v184, v[24:27] offset:18688
	v_cndmask_b32_e64 v104, v24, v26, s[94:95]
	v_cndmask_b32_e64 v105, v25, v27, s[94:95]
	v_mov_b32_dpp v106, v24 row_shl:8 row_mask:0xf bank_mask:0x3
	v_mov_b32_dpp v107, v25 row_shl:8 row_mask:0xf bank_mask:0x3
	v_mov_b32_dpp v106, v26 row_shr:8 row_mask:0xf bank_mask:0xc
	v_mov_b32_dpp v107, v27 row_shr:8 row_mask:0xf bank_mask:0xc
	s_nop 1
	v_perm_b32 v108, v106, v104, v96
	v_perm_b32 v109, v106, v104, v97
	v_perm_b32 v110, v107, v105, v96
	v_perm_b32 v111, v107, v105, v97
	ds_write_b32 v98, v108 offset:55552
	ds_write_b32 v98, v109 offset:55696
	ds_write_b32 v98, v110 offset:55840
	ds_write_b32 v98, v111 offset:55984
	v_cvt_pk_bf16_f32 v24, v59, v58
	v_cvt_pk_bf16_f32 v25, v56, v65
	v_cvt_pk_bf16_f32 v26, v46, v47
	v_cvt_pk_bf16_f32 v27, v32, v41
	ds_write_b128 v184, v[24:27] offset:27904
	v_cvt_pk_bf16_f32 v27, v30, v31
	v_cvt_pk_bf16_f32 v24, v20, v21
	v_cvt_pk_bf16_f32 v25, v22, v23
	v_cvt_pk_bf16_f32 v26, v18, v19
	v_cndmask_b32_e64 v104, v27, v25, s[94:95]
	v_cndmask_b32_e64 v105, v26, v24, s[94:95]
	v_mov_b32_dpp v106, v27 row_shl:8 row_mask:0xf bank_mask:0x3
	v_mov_b32_dpp v107, v26 row_shl:8 row_mask:0xf bank_mask:0x3
	v_mov_b32_dpp v106, v25 row_shr:8 row_mask:0xf bank_mask:0xc
	v_mov_b32_dpp v107, v24 row_shr:8 row_mask:0xf bank_mask:0xc
	s_nop 1
	v_perm_b32 v108, v106, v104, v96
	v_perm_b32 v109, v106, v104, v97
	v_perm_b32 v110, v107, v105, v96
	v_perm_b32 v111, v107, v105, v97
	ds_write_b32 v98, v108 offset:64768
	ds_write_b32 v98, v109 offset:64912
	ds_write_b32 v98, v110 offset:65056
	ds_write_b32 v98, v111 offset:65200
